# lane-parallel max|gain| for the two attention softmax-shift bounds (was a 16-iteration loop with one memory round trip per iteration)
# speedup vs baseline: 1.0141x; 1.0141x over previous
.LBB0_1042:
	s_waitcnt lgkmcnt(0)
	v_readfirstlane_b32 s4, v2
	v_readfirstlane_b32 s5, v3
	v_readfirstlane_b32 s6, v4
	v_readfirstlane_b32 s7, v5
	v_min_u32_e32 v8, 47, v198
	v_lshlrev_b32_e32 v8, 3, v8
	s_nop 3
	global_load_dwordx2 v[10:11], v8, s[4:5]
	global_load_dwordx2 v[12:13], v8, s[6:7]
	s_waitcnt vmcnt(0)
	v_max_f32_e64 v1, |v10|, |v11|
	v_max_f32_e64 v7, |v12|, |v13|
	s_nop 1
	v_max_f32_dpp v1, v1, v1 quad_perm:[1,0,3,2] row_mask:0xf bank_mask:0xf bound_ctrl:1
	v_max_f32_dpp v7, v7, v7 quad_perm:[1,0,3,2] row_mask:0xf bank_mask:0xf bound_ctrl:1
	s_nop 1
	v_max_f32_dpp v1, v1, v1 quad_perm:[2,3,0,1] row_mask:0xf bank_mask:0xf bound_ctrl:1
	v_max_f32_dpp v7, v7, v7 quad_perm:[2,3,0,1] row_mask:0xf bank_mask:0xf bound_ctrl:1
	s_nop 1
	v_max_f32_dpp v1, v1, v1 row_half_mirror row_mask:0xf bank_mask:0xf bound_ctrl:1
	v_max_f32_dpp v7, v7, v7 row_half_mirror row_mask:0xf bank_mask:0xf bound_ctrl:1
	s_nop 1
	v_max_f32_dpp v1, v1, v1 row_mirror row_mask:0xf bank_mask:0xf bound_ctrl:1
	v_max_f32_dpp v7, v7, v7 row_mirror row_mask:0xf bank_mask:0xf bound_ctrl:1
	s_nop 1
	v_readlane_b32 s98, v1, 0
	v_readlane_b32 s99, v1, 16
	v_readlane_b32 s100, v1, 32
	v_readlane_b32 s101, v1, 48
	s_nop 1
	v_mov_b32_e32 v1, s98
	v_max_f32_e32 v1, s99, v1
	v_max_f32_e32 v1, s100, v1
	v_max_f32_e32 v1, s101, v1
	s_nop 1
	v_readlane_b32 s98, v7, 0
	v_readlane_b32 s99, v7, 16
	v_readlane_b32 s100, v7, 32
	v_readlane_b32 s101, v7, 48
	s_nop 1
	v_mov_b32_e32 v7, s98
	v_max_f32_e32 v7, s99, v7
	v_max_f32_e32 v7, s100, v7
	v_max_f32_e32 v7, s101, v7
	s_add_u32 s38, s34, 0x3d28000
	s_addc_u32 s39, s35, 0
	s_add_u32 s12, s34, 0xb4e8000
	s_addc_u32 s13, s35, 0
	s_add_u32 s14, s34, 0xbf68000
	s_addc_u32 s15, s35, 0
	s_cmpk_lg_i32 s56, 0x100
	s_cselect_b64 s[4:5], -1, 0
	s_add_i32 s2, 0, 0x10400
	v_lshl_add_u32 v5, v198, 2, s2
	s_lshl_b32 s2, s30, 5
	v_and_b32_e32 v104, 48, v198
	v_mov_b32_e32 v105, 0
	v_mul_f32_e32 v1, 0x411cc471, v1
	s_and_b32 s18, s2, 0xe0
	v_lshl_add_u64 v[2:3], s[34:35], 0, v[104:105]
	s_mov_b64 s[2:3], 0xabe8000
	v_mul_f32_e32 v1, v1, v7
	v_lshl_add_u64 v[106:107], v[2:3], 0, s[2:3]
	s_mov_b32 s2, 0x15555556
	v_or_b32_e32 v7, 0x200, v0
	v_or_b32_e32 v6, 0x400, v0
	v_mul_hi_u32 v144, v0, s2
	v_mul_hi_u32 v145, v7, s2
	v_mul_hi_u32 v146, v6, s2
	v_mul_u32_u24_e32 v2, 12, v144
	v_mul_u32_u24_e32 v4, 12, v145
	v_mul_u32_u24_e32 v9, 12, v146
	v_sub_u32_e32 v3, v0, v2
	v_sub_u32_e32 v8, v7, v4
	v_sub_u32_e32 v9, v6, v9
	v_lshlrev_b32_e32 v14, 3, v0
	s_add_i32 s2, 0, 0x15400
	v_mul_f32_e32 v140, 0x3fb8aa3b, v1
	s_ashr_i32 s17, s30, 3
	v_and_b32_e32 v1, 15, v0
	v_lshrrev_b32_e32 v103, 4, v198
	v_lshlrev_b32_e32 v2, 3, v3
	v_lshlrev_b32_e32 v4, 3, v8
	v_lshlrev_b32_e32 v6, 3, v9
	v_lshrrev_b32_e32 v99, 3, v0
	v_and_b32_e32 v101, 7, v0
	v_lshrrev_b32_e32 v147, 3, v7
	v_bitop3_b32 v3, v144, v3, 15 bitop3:0x6c
	v_bitop3_b32 v8, v145, v8, 15 bitop3:0x6c
	v_bitop3_b32 v9, v146, v9, 15 bitop3:0x6c
	s_movk_i32 s22, 0xa0
	v_and_b32_e32 v142, 24, v14
	v_mov_b32_e32 v14, s2
	s_and_b32 s19, s17, -2
	v_lshl_add_u32 v7, v144, 8, 0
	v_lshlrev_b32_e32 v3, 4, v3
	v_lshl_add_u32 v10, v145, 8, 0
	v_lshlrev_b32_e32 v8, 4, v8
	v_lshl_add_u32 v11, v146, 8, 0
	v_lshlrev_b32_e32 v9, 4, v9
	v_mad_u32_u24 v12, v99, s22, 0
	v_lshlrev_b32_e32 v102, 4, v101
	v_mad_u32_u24 v13, v147, s22, 0
	v_lshlrev_b32_e32 v98, 2, v103
	v_bfe_u32 v141, v0, 2, 2
	v_mad_u32_u24 v15, v99, s22, v14
	v_mad_u32_u24 v14, v147, s22, v14
	v_lshl_add_u32 v149, v198, 4, 0
	s_lshl_b32 s6, s68, 7
	v_lshl_add_u32 v16, v1, 2, 0
	v_lshlrev_b32_e32 v118, 1, v2
	v_mbcnt_lo_u32_b32 v2, -1, 0
	s_mov_b32 s16, 0x3fb8aa3b
	s_mov_b32 s7, 0
	s_addk_i32 s19, 0x100
	s_and_b32 s20, s17, -16
	v_lshlrev_b32_e32 v138, 3, v103
	s_movk_i32 s21, 0x600
	v_mul_u32_u24_e32 v108, 0x600, v144
	v_mov_b32_e32 v109, v105
	v_mul_u32_u24_e32 v110, 0x600, v145
	v_mov_b32_e32 v111, v105
	v_mul_u32_u24_e32 v112, 0x600, v146
	v_mov_b32_e32 v113, v105
	v_lshlrev_b32_e32 v114, 10, v99
	v_mov_b32_e32 v115, v105
	v_lshlrev_b32_e32 v100, 3, v101
	v_lshlrev_b32_e32 v116, 10, v147
	v_mov_b32_e32 v117, v105
	v_or_b32_e32 v139, 4, v103
	v_or_b32_e32 v148, 8, v103
	v_cmp_gt_u32_e64 s[2:3], 16, v198
	s_lshl_b32 s23, s68, 13
	v_or_b32_e32 v150, v141, v98
	v_add_u32_e32 v151, 0x10400, v16
	v_add_u32_e32 v152, 0x400, v149
	v_add_u32_e32 v153, 0x800, v149
	v_add_u32_e32 v154, 0xc00, v149
	v_add_u32_e32 v155, 0x1000, v149
	v_add_u32_e32 v156, 0x10440, v16
	v_add_u32_e32 v157, 0x1400, v149
	v_lshlrev_b32_e32 v120, 1, v4
	v_lshlrev_b32_e32 v122, 1, v6
	s_mov_b32 s24, 0x30000
	s_mov_b32 s25, 0x20000
	v_add_u32_e32 v158, v15, v102
	v_add_u32_e32 v159, v14, v102
	v_add_u32_e32 v160, v7, v3
	v_add_u32_e32 v161, v10, v8
	v_add_u32_e32 v162, v11, v9
	v_add_u32_e32 v163, v12, v102
	v_add_u32_e32 v164, v13, v102
	v_mbcnt_hi_u32_b32 v143, -1, v2
	v_add_u32_e32 v165, s6, v5
	s_mov_b32 s10, 0
	s_mov_b32 s26, 0
	s_branch .LBB0_1045

.LBB0_2792:
	v_readfirstlane_b32 s8, v2
	v_readfirstlane_b32 s9, v3
	v_readfirstlane_b32 s10, v4
	v_readfirstlane_b32 s11, v5
	v_lshlrev_b32_e32 v9, 2, v198
	s_nop 4
	global_load_dword v6, v9, s[8:9]
	global_load_dword v7, v9, s[10:11]
	s_waitcnt vmcnt(0)
	v_and_b32_e32 v6, 0x7fffffff, v6
	v_and_b32_e32 v7, 0x7fffffff, v7
	s_nop 1
	v_max_f32_dpp v6, v6, v6 quad_perm:[1,0,3,2] row_mask:0xf bank_mask:0xf bound_ctrl:1
	v_max_f32_dpp v7, v7, v7 quad_perm:[1,0,3,2] row_mask:0xf bank_mask:0xf bound_ctrl:1
	s_nop 1
	v_max_f32_dpp v6, v6, v6 quad_perm:[2,3,0,1] row_mask:0xf bank_mask:0xf bound_ctrl:1
	v_max_f32_dpp v7, v7, v7 quad_perm:[2,3,0,1] row_mask:0xf bank_mask:0xf bound_ctrl:1
	s_nop 1
	v_max_f32_dpp v6, v6, v6 row_half_mirror row_mask:0xf bank_mask:0xf bound_ctrl:1
	v_max_f32_dpp v7, v7, v7 row_half_mirror row_mask:0xf bank_mask:0xf bound_ctrl:1
	s_nop 1
	v_max_f32_dpp v6, v6, v6 row_mirror row_mask:0xf bank_mask:0xf bound_ctrl:1
	v_max_f32_dpp v7, v7, v7 row_mirror row_mask:0xf bank_mask:0xf bound_ctrl:1
	s_nop 1
	v_readlane_b32 s98, v6, 0
	v_readlane_b32 s99, v6, 16
	v_readlane_b32 s100, v6, 32
	v_readlane_b32 s101, v6, 48
	s_nop 1
	v_mov_b32_e32 v6, s98
	v_max_f32_e32 v6, s99, v6
	v_max_f32_e32 v6, s100, v6
	v_max_f32_e32 v6, s101, v6
	s_nop 1
	v_readlane_b32 s98, v7, 0
	v_readlane_b32 s99, v7, 16
	v_readlane_b32 s100, v7, 32
	v_readlane_b32 s101, v7, 48
	s_nop 1
	v_mov_b32_e32 v7, s98
	v_max_f32_e32 v7, s99, v7
	v_max_f32_e32 v7, s100, v7
	v_max_f32_e32 v7, s101, v7
	s_add_u32 s14, s2, 0xaa28000
	s_addc_u32 s15, s3, 0
	s_add_u32 s16, s2, 0xa328000
	s_addc_u32 s17, s3, 0
	v_mul_f32_e32 v2, 0x41000000, v6
	s_add_u32 s6, s2, 0xe5a8000
	v_mul_f32_e32 v2, v2, v7
	v_and_b32_e32 v106, 48, v198
	v_mov_b32_e32 v107, 0
	v_or_b32_e32 v6, 0x200, v0
	s_addc_u32 s7, s3, 0
	v_mul_f32_e32 v136, 0x3fb8aa3b, v2
	v_lshl_add_u64 v[2:3], s[2:3], 0, v[106:107]
	s_mov_b64 s[2:3], 0x9d28000
	v_lshrrev_b32_e32 v138, 3, v0
	v_lshrrev_b32_e32 v139, 3, v6
	v_lshrrev_b32_e32 v140, 4, v6
	v_or_b32_e32 v6, 0x600, v0
	v_lshl_add_u64 v[108:109], v[2:3], 0, s[2:3]
	v_lshrrev_b32_e32 v142, 4, v6
	v_lshlrev_b32_e32 v6, 8, v138
	v_lshlrev_b32_e32 v9, 8, v139
	s_add_i32 s2, 0, 0x11400
	v_add_u32_e32 v7, 0, v6
	v_add_u32_e32 v10, 0, v9
	v_lshlrev_b32_e32 v15, 3, v0
	v_add_u32_e32 v6, s2, v6
	v_add_u32_e32 v9, s2, v9
	s_add_i32 s2, 0, 0x19400
	s_add_i32 s8, 0, 0x20400
	v_lshrrev_b32_e32 v137, 4, v198
	v_and_b32_e32 v3, 7, v0
	s_movk_i32 s23, 0x120
	v_and_b32_e32 v145, 24, v15
	v_mov_b32_e32 v15, s2
	v_lshl_add_u32 v5, v198, 2, s8
	s_ashr_i32 s19, s30, 3
	s_lshl_b32 s8, s30, 5
	v_lshlrev_b32_e32 v2, 3, v3
	v_bitop3_b32 v8, v138, v3, 15 bitop3:0x6c
	v_bitop3_b32 v3, v139, v3, 15 bitop3:0x6c
	v_lshlrev_b32_e32 v144, 2, v137
	v_lshrrev_b32_e32 v14, 2, v1
	v_mad_u32_u24 v147, v199, s23, v15
	s_and_b32 s20, s8, 0xe0
	s_and_b32 s21, s19, -2
	v_lshlrev_b32_e32 v4, 3, v1
	v_or_b32_e32 v141, 64, v199
	v_lshlrev_b32_e32 v8, 4, v8
	v_lshlrev_b32_e32 v3, 4, v3
	v_mad_u32_u24 v11, v199, s23, 0
	v_lshlrev_b32_e32 v143, 4, v1
	v_mad_u32_u24 v12, v140, s23, 0
	v_mad_u32_u24 v13, v142, s23, 0
	v_mad_u32_u24 v16, v140, s23, v15
	v_add_u32_e32 v17, 0x4800, v147
	v_mad_u32_u24 v15, v142, s23, v15
	v_lshl_add_u32 v148, v198, 4, 0
	s_lshl_b32 s8, s68, 7
	v_or_b32_e32 v149, v14, v144
	v_lshl_add_u32 v14, v1, 2, 0
	v_lshlrev_b32_e32 v122, 1, v2
	v_mbcnt_lo_u32_b32 v2, -1, 0
	s_mov_b32 s18, 0x3fb8aa3b
	s_mov_b32 s9, 0
	s_addk_i32 s21, 0x100
	s_and_b32 s22, s19, -16
	v_lshlrev_b32_e32 v110, 10, v138
	v_mov_b32_e32 v111, v107
	v_lshlrev_b32_e32 v112, 10, v139
	v_mov_b32_e32 v113, v107
	v_lshlrev_b32_e32 v114, 10, v199
	v_mov_b32_e32 v115, v107
	v_lshlrev_b32_e32 v116, 10, v140
	v_mov_b32_e32 v117, v107
	v_lshlrev_b32_e32 v118, 10, v141
	v_mov_b32_e32 v119, v107
	v_lshlrev_b32_e32 v120, 10, v142
	v_mov_b32_e32 v121, v107
	v_or_b32_e32 v146, 4, v137
	v_cmp_gt_u32_e64 s[2:3], 16, v198
	s_lshl_b32 s24, s68, 14
	v_add_u32_e32 v150, 0x20400, v14
	v_add_u32_e32 v151, 0x400, v148
	v_add_u32_e32 v152, 0x800, v148
	v_add_u32_e32 v153, 0xc00, v148
	v_add_u32_e32 v154, 0x1000, v148
	v_add_u32_e32 v155, 0x20440, v14
	v_add_u32_e32 v156, 0x2400, v148
	v_lshlrev_b32_e32 v124, 1, v4
	v_add_u32_e32 v157, v6, v8
	v_add_u32_e32 v158, v9, v3
	v_add_u32_e32 v159, v16, v143
	v_add_u32_e32 v160, v17, v143
	v_add_u32_e32 v161, v15, v143
	v_add_u32_e32 v162, v7, v8
	v_add_u32_e32 v163, v10, v3
	v_add_u32_e32 v164, v11, v143
	v_add_u32_e32 v165, v12, v143
	v_add_u32_e32 v166, v13, v143
	v_mbcnt_hi_u32_b32 v167, -1, v2
	v_add_u32_e32 v168, s8, v5
	s_mov_b32 s12, 0
	s_mov_b32 s25, 0
	s_branch .LBB0_2795
